# second norm_rows loop copy: shift/scale vectors loaded once per iteration at loop top (same fix as previous version)
# speedup vs baseline: 1.0085x; 1.0013x over previous
; __device__ __forceinline__ unsigned pk2(float lo, float hi) { return pg8::pk_bf16_rne(lo, hi); }
; __device__ __forceinline__ float wave_sum(float v) { v = row16_allsum(v); v = rows_pair_sum(v); v = halves_pair_sum(v); return v; }
; __device__ __forceinline__ void norm_rows(const Params& P, const float* src, float* copy_dst, int l, int shi, int gw, int NGW, int lane) {
;     ...
;     for (int m0 = 2 * gw; m0 < T; m0 += 2 * NGW) {
;         f32x4 v[2][4]; float s[2] = {0.f, 0.f};
; #pragma unroll
;         for (int q = 0; q < 2; ++q) { const f32x4* xr = (const f32x4*)(src + (size_t)(m0 + q) * D) + lane;
; #pragma unroll
;             for (int j = 0; j < 4; ++j) v[q][j] = xr[64 * j]; }
; #pragma unroll
;         for (int q = 0; q < 2; ++q) {
; #pragma unroll
;             for (int j = 0; j < 4; ++j) s[q] += (v[q][j].x * v[q][j].x + v[q][j].y * v[q][j].y) + (v[q][j].z * v[q][j].z + v[q][j].w * v[q][j].w); }
; #pragma unroll
;         for (int q = 0; q < 2; ++q) {
;             const int m = m0 + q, b = m >> 12;
;             const float rstd = 1.0f / sqrtf(wave_sum(s[q]) * (1.0f / D) + 1e-6f);
;             const f32x4* sh = (const f32x4*)(modl + (size_t)b * 9216 + shi * 1024) + lane;
;             const f32x4* sc = (const f32x4*)(modl + (size_t)b * 9216 + (shi + 1) * 1024) + lane;
;             u32x2* o8 = (u32x2*)(H + (size_t)m * D) + lane;
; #pragma unroll
;             for (int j = 0; j < 4; ++j) { const f32x4 a = sh[64 * j], c = sc[64 * j]; const f32x4 o = v[q][j] * rstd * (c + 1.0f) + a;
;                 u32x2 w; w.x = pk2(o.x, o.y); w.y = pk2(o.z, o.w); o8[64 * j] = w; }
.LBB0_418:
	v_ashrrev_i32_e32 v100, 12, v20
	v_mul_hi_i32_i24_e32 v101, 0x9000, v100
	v_mul_i32_i24_e32 v100, 0x9000, v100
	v_lshl_add_u64 v[100:101], s[8:9], 0, v[100:101]
	v_lshl_add_u64 v[102:103], v[100:101], 0, v[152:153]
	v_lshl_add_u64 v[104:105], v[102:103], 0, s[20:21]
	global_load_dwordx4 v[60:63], v[102:103], off
	global_load_dwordx4 v[64:67], v[102:103], off offset:1024
	global_load_dwordx4 v[68:71], v[102:103], off offset:2048
	global_load_dwordx4 v[72:75], v[102:103], off offset:3072
	global_load_dwordx4 v[76:79], v[104:105], off
	global_load_dwordx4 v[80:83], v[104:105], off offset:1024
	global_load_dwordx4 v[84:87], v[104:105], off offset:2048
	global_load_dwordx4 v[88:91], v[104:105], off offset:3072
	global_load_dwordx4 v[30:33], v[24:25], off offset:-4096
	global_load_dwordx4 v[34:37], v[24:25], off offset:-3072
	global_load_dwordx4 v[38:41], v[24:25], off offset:-2048
	global_load_dwordx4 v[16:19], v[24:25], off offset:-1024
	global_load_dwordx4 v[12:15], v[24:25], off
	global_load_dwordx4 v[8:11], v[24:25], off offset:1024
	global_load_dwordx4 v[4:7], v[24:25], off offset:2048
	global_load_dwordx4 v[0:3], v[24:25], off offset:3072
	v_ashrrev_i32_e32 v21, 12, v20
	v_mul_hi_i32_i24_e32 v27, 0x9000, v21
	v_mul_i32_i24_e32 v26, 0x9000, v21
	v_lshl_add_u64 v[26:27], s[8:9], 0, v[26:27]
	v_lshl_add_u64 v[26:27], v[26:27], 0, v[152:153]
	v_add_co_u32_e32 v50, vcc, s36, v26
	v_lshl_add_u64 v[28:29], v[26:27], 0, s[20:21]
	s_nop 0
	v_addc_co_u32_e32 v51, vcc, 0, v27, vcc
	v_add_u32_e32 v20, s28, v20
	v_lshl_add_u64 v[24:25], v[24:25], 0, s[14:15]
	s_waitcnt vmcnt(7)
	v_mul_f32_e32 v21, v31, v31
	v_mul_f32_e32 v52, v33, v33
	s_waitcnt vmcnt(6)
	v_mul_f32_e32 v53, v35, v35
	v_mul_f32_e32 v54, v37, v37
	s_waitcnt vmcnt(5)
	v_mul_f32_e32 v55, v39, v39
	v_mul_f32_e32 v56, v41, v41
	v_fmac_f32_e32 v21, v30, v30
	v_fmac_f32_e32 v52, v32, v32
	v_fmac_f32_e32 v53, v34, v34
	v_fmac_f32_e32 v54, v36, v36
	s_waitcnt vmcnt(4)
	v_mul_f32_e32 v57, v17, v17
	v_mul_f32_e32 v58, v19, v19
	v_fmac_f32_e32 v55, v38, v38
	v_fmac_f32_e32 v56, v40, v40
	v_add_f32_e32 v21, v21, v52
	v_add_f32_e32 v52, v53, v54
	v_fmac_f32_e32 v57, v16, v16
	v_fmac_f32_e32 v58, v18, v18
	v_add_f32_e32 v53, v55, v56
	v_add_f32_e32 v21, v21, v52
	v_add_f32_e32 v54, v57, v58
	v_add_f32_e32 v21, v21, v53
	v_add_f32_e32 v21, v21, v54
	s_waitcnt vmcnt(0)
	v_mov_b64_e32 v[42:43], v[60:61]
	v_mov_b64_e32 v[44:45], v[62:63]
	v_mov_b64_e32 v[46:47], v[76:77]
	v_mov_b64_e32 v[48:49], v[78:79]
	v_pk_add_f32 v[48:49], v[48:49], 1.0 op_sel_hi:[1,0]
	v_pk_add_f32 v[46:47], v[46:47], 1.0 op_sel_hi:[1,0]
	v_add_f32_dpp v21, v21, v21 row_ror:8 row_mask:0xf bank_mask:0xf bound_ctrl:1
	s_nop 1
	v_add_f32_dpp v21, v21, v21 row_ror:4 row_mask:0xf bank_mask:0xf bound_ctrl:1
	s_nop 1
	v_add_f32_dpp v21, v21, v21 row_ror:2 row_mask:0xf bank_mask:0xf bound_ctrl:1
	s_nop 1
	v_add_f32_dpp v21, v21, v21 row_ror:1 row_mask:0xf bank_mask:0xf bound_ctrl:1
	v_mov_b32_e32 v52, v21
	s_nop 1
	v_permlane16_swap_b32_e32 v21, v52
	v_add_f32_e32 v21, v21, v52
	v_mov_b32_e32 v52, v21
	s_nop 1
	v_permlane32_swap_b32_e32 v21, v52
	v_add_f32_e32 v21, v21, v52
	v_fmamk_f32 v21, v21, 0x3a800000, v155
	v_mul_f32_e32 v52, 0x4f800000, v21
	v_cmp_gt_f32_e32 vcc, s43, v21
	s_nop 1
	v_cndmask_b32_e32 v21, v21, v52, vcc
	v_sqrt_f32_e32 v52, v21
	s_nop 0
	v_add_u32_e32 v53, -1, v52
	v_add_u32_e32 v54, 1, v52
	v_fma_f32 v55, -v53, v52, v21
	v_fma_f32 v56, -v54, v52, v21
	v_cmp_ge_f32_e64 s[4:5], 0, v55
	s_nop 1
	v_cndmask_b32_e64 v52, v52, v53, s[4:5]
	v_cmp_lt_f32_e64 s[4:5], 0, v56
	s_nop 1
	v_cndmask_b32_e64 v52, v52, v54, s[4:5]
	v_mul_f32_e32 v53, 0x37800000, v52
	v_cndmask_b32_e32 v52, v52, v53, vcc
	v_cmp_class_f32_e32 vcc, v21, v175
	s_nop 1
	v_cndmask_b32_e32 v21, v52, v21, vcc
	v_div_scale_f32 v52, s[4:5], v21, v21, 1.0
	v_rcp_f32_e32 v54, v52
	v_div_scale_f32 v53, vcc, 1.0, v21, 1.0
	v_fma_f32 v55, -v52, v54, 1.0
	v_fmac_f32_e32 v54, v55, v54
	v_mul_f32_e32 v55, v53, v54
	v_fma_f32 v56, -v52, v55, v53
	v_fmac_f32_e32 v55, v56, v54
	v_fma_f32 v52, -v52, v55, v53
	v_div_fmas_f32 v52, v52, v54, v55
	v_div_fixup_f32 v52, v52, v21, 1.0
	v_pk_mul_f32 v[30:31], v[30:31], v[52:53] op_sel_hi:[1,0]
	v_pk_mul_f32 v[32:33], v[32:33], v[52:53] op_sel_hi:[1,0]
	v_pk_fma_f32 v[30:31], v[46:47], v[30:31], v[42:43]
	v_pk_fma_f32 v[32:33], v[48:49], v[32:33], v[44:45]
	v_cvt_pk_bf16_f32 v30, v30, v31
	v_cvt_pk_bf16_f32 v31, v32, v33
	global_store_dwordx2 v[22:23], v[30:31], off offset:-3584
	s_nop 1
	v_mov_b64_e32 v[30:31], v[80:81]
	v_mov_b64_e32 v[32:33], v[82:83]
	s_nop 0
	v_mov_b64_e32 v[42:43], v[64:65]
	v_mov_b64_e32 v[44:45], v[66:67]
	v_pk_mul_f32 v[34:35], v[34:35], v[52:53] op_sel_hi:[1,0]
	v_pk_mul_f32 v[36:37], v[36:37], v[52:53] op_sel_hi:[1,0]
	v_pk_mul_f32 v[38:39], v[38:39], v[52:53] op_sel_hi:[1,0]
	v_pk_mul_f32 v[40:41], v[40:41], v[52:53] op_sel_hi:[1,0]
	v_pk_mul_f32 v[16:17], v[16:17], v[52:53] op_sel_hi:[1,0]
	v_pk_mul_f32 v[18:19], v[18:19], v[52:53] op_sel_hi:[1,0]
	v_mul_f32_e32 v21, v13, v13
	v_fmac_f32_e32 v21, v12, v12
	v_pk_add_f32 v[32:33], v[32:33], 1.0 op_sel_hi:[1,0]
	v_pk_add_f32 v[30:31], v[30:31], 1.0 op_sel_hi:[1,0]
	v_pk_fma_f32 v[32:33], v[32:33], v[36:37], v[44:45]
	v_pk_fma_f32 v[30:31], v[30:31], v[34:35], v[42:43]
	v_mul_f32_e32 v42, v7, v7
	v_cvt_pk_bf16_f32 v30, v30, v31
	v_cvt_pk_bf16_f32 v31, v32, v33
	global_store_dwordx2 v[22:23], v[30:31], off offset:-3072
	s_nop 1
	v_mov_b64_e32 v[30:31], v[84:85]
	v_mov_b64_e32 v[32:33], v[86:87]
	s_nop 0
	v_mov_b64_e32 v[34:35], v[68:69]
; __device__ __forceinline__ unsigned pk2(float lo, float hi) { return pg8::pk_bf16_rne(lo, hi); }
; __device__ __forceinline__ float wave_sum(float v) { v = row16_allsum(v); v = rows_pair_sum(v); v = halves_pair_sum(v); return v; }
; __device__ __forceinline__ void norm_rows(const Params& P, const float* src, float* copy_dst, int l, int shi, int gw, int NGW, int lane) {
;     ...
;             for (int j = 0; j < 4; ++j) s[q] += (v[q][j].x * v[q][j].x + v[q][j].y * v[q][j].y) + (v[q][j].z * v[q][j].z + v[q][j].w * v[q][j].w); }
; #pragma unroll
;         for (int q = 0; q < 2; ++q) {
;             const int m = m0 + q, b = m >> 12;
;             const float rstd = 1.0f / sqrtf(wave_sum(s[q]) * (1.0f / D) + 1e-6f);
;             const f32x4* sh = (const f32x4*)(modl + (size_t)b * 9216 + shi * 1024) + lane;
;             const f32x4* sc = (const f32x4*)(modl + (size_t)b * 9216 + (shi + 1) * 1024) + lane;
;             u32x2* o8 = (u32x2*)(H + (size_t)m * D) + lane;
; #pragma unroll
;             for (int j = 0; j < 4; ++j) { const f32x4 a = sh[64 * j], c = sc[64 * j]; const f32x4 o = v[q][j] * rstd * (c + 1.0f) + a;
;                 u32x2 w; w.x = pk2(o.x, o.y); w.y = pk2(o.z, o.w); o8[64 * j] = w; }
	v_mov_b64_e32 v[36:37], v[70:71]
	v_mul_f32_e32 v43, v1, v1
	v_mul_f32_e32 v44, v3, v3
	v_fmac_f32_e32 v42, v6, v6
	v_fmac_f32_e32 v43, v0, v0
	v_fmac_f32_e32 v44, v2, v2
	v_pk_add_f32 v[32:33], v[32:33], 1.0 op_sel_hi:[1,0]
	v_pk_add_f32 v[30:31], v[30:31], 1.0 op_sel_hi:[1,0]
	v_pk_fma_f32 v[32:33], v[32:33], v[40:41], v[36:37]
	v_pk_fma_f32 v[30:31], v[30:31], v[38:39], v[34:35]
	v_mul_f32_e32 v38, v15, v15
	v_cvt_pk_bf16_f32 v30, v30, v31
	v_cvt_pk_bf16_f32 v31, v32, v33
	global_store_dwordx2 v[22:23], v[30:31], off offset:-2560
	s_nop 1
	v_mov_b64_e32 v[30:31], v[88:89]
	v_mov_b64_e32 v[32:33], v[90:91]
	s_nop 0
	v_mov_b64_e32 v[34:35], v[72:73]
	v_mov_b64_e32 v[36:37], v[74:75]
	v_mul_f32_e32 v39, v9, v9
	v_mul_f32_e32 v40, v11, v11
	v_mul_f32_e32 v41, v5, v5
	v_fmac_f32_e32 v38, v14, v14
	v_fmac_f32_e32 v39, v8, v8
	v_fmac_f32_e32 v40, v10, v10
	v_fmac_f32_e32 v41, v4, v4
	v_add_f32_e32 v21, v21, v38
	v_pk_add_f32 v[32:33], v[32:33], 1.0 op_sel_hi:[1,0]
	v_pk_add_f32 v[30:31], v[30:31], 1.0 op_sel_hi:[1,0]
	v_pk_fma_f32 v[18:19], v[18:19], v[32:33], v[36:37]
	v_pk_fma_f32 v[16:17], v[16:17], v[30:31], v[34:35]
	v_add_f32_e32 v34, v39, v40
	v_cvt_pk_bf16_f32 v16, v16, v17
	v_cvt_pk_bf16_f32 v17, v18, v19
	global_store_dwordx2 v[22:23], v[16:17], off offset:-2048
	s_nop 1
	v_mov_b64_e32 v[16:17], v[76:77]
	v_mov_b64_e32 v[18:19], v[78:79]
	s_nop 0
	v_mov_b64_e32 v[30:31], v[60:61]
	v_mov_b64_e32 v[32:33], v[62:63]
	v_add_f32_e32 v35, v41, v42
	v_add_f32_e32 v21, v21, v34
	v_add_f32_e32 v36, v43, v44
	v_add_f32_e32 v21, v21, v35
	v_add_f32_e32 v21, v21, v36
	v_pk_add_f32 v[18:19], v[18:19], 1.0 op_sel_hi:[1,0]
	v_add_f32_dpp v21, v21, v21 row_ror:8 row_mask:0xf bank_mask:0xf bound_ctrl:1
	v_pk_add_f32 v[16:17], v[16:17], 1.0 op_sel_hi:[1,0]
	s_nop 0
	v_add_f32_dpp v21, v21, v21 row_ror:4 row_mask:0xf bank_mask:0xf bound_ctrl:1
	s_nop 1
	v_add_f32_dpp v21, v21, v21 row_ror:2 row_mask:0xf bank_mask:0xf bound_ctrl:1
	s_nop 1
	v_add_f32_dpp v21, v21, v21 row_ror:1 row_mask:0xf bank_mask:0xf bound_ctrl:1
	v_mov_b32_e32 v34, v21
	s_nop 1
	v_permlane16_swap_b32_e32 v21, v34
	v_add_f32_e32 v21, v21, v34
	v_mov_b32_e32 v34, v21
	s_nop 1
	v_permlane32_swap_b32_e32 v21, v34
	v_add_f32_e32 v21, v21, v34
	v_fmamk_f32 v21, v21, 0x3a800000, v155
	v_mul_f32_e32 v34, 0x4f800000, v21
	v_cmp_gt_f32_e32 vcc, s43, v21
	s_nop 1
	v_cndmask_b32_e32 v21, v21, v34, vcc
	v_sqrt_f32_e32 v34, v21
	s_nop 0
	v_add_u32_e32 v35, -1, v34
	v_add_u32_e32 v36, 1, v34
	v_fma_f32 v37, -v35, v34, v21
	v_fma_f32 v38, -v36, v34, v21
	v_cmp_ge_f32_e64 s[4:5], 0, v37
	s_nop 1
	v_cndmask_b32_e64 v34, v34, v35, s[4:5]
	v_cmp_lt_f32_e64 s[4:5], 0, v38
	s_nop 1
	v_cndmask_b32_e64 v34, v34, v36, s[4:5]
	v_mul_f32_e32 v35, 0x37800000, v34
	v_cndmask_b32_e32 v34, v34, v35, vcc
	v_cmp_class_f32_e32 vcc, v21, v175
	s_nop 1
	v_cndmask_b32_e32 v21, v34, v21, vcc
	v_div_scale_f32 v34, s[4:5], v21, v21, 1.0
	v_rcp_f32_e32 v36, v34
	v_div_scale_f32 v35, vcc, 1.0, v21, 1.0
	v_fma_f32 v37, -v34, v36, 1.0
	v_fmac_f32_e32 v36, v37, v36
	v_mul_f32_e32 v37, v35, v36
	v_fma_f32 v38, -v34, v37, v35
	v_fmac_f32_e32 v37, v38, v36
	v_fma_f32 v34, -v34, v37, v35
	v_div_fmas_f32 v34, v34, v36, v37
	v_div_fixup_f32 v34, v34, v21, 1.0
	v_pk_mul_f32 v[12:13], v[12:13], v[34:35] op_sel_hi:[1,0]
	v_pk_mul_f32 v[14:15], v[14:15], v[34:35] op_sel_hi:[1,0]
	v_pk_fma_f32 v[12:13], v[16:17], v[12:13], v[30:31]
	v_pk_fma_f32 v[14:15], v[18:19], v[14:15], v[32:33]
	v_cvt_pk_bf16_f32 v12, v12, v13
	v_cvt_pk_bf16_f32 v13, v14, v15
	global_store_dwordx2 v[22:23], v[12:13], off offset:-1536
	s_nop 1
	v_mov_b64_e32 v[12:13], v[80:81]
	v_mov_b64_e32 v[14:15], v[82:83]
	s_nop 0
	v_mov_b64_e32 v[16:17], v[64:65]
	v_mov_b64_e32 v[18:19], v[66:67]
	v_pk_mul_f32 v[8:9], v[8:9], v[34:35] op_sel_hi:[1,0]
	v_pk_mul_f32 v[10:11], v[10:11], v[34:35] op_sel_hi:[1,0]
	v_pk_mul_f32 v[4:5], v[4:5], v[34:35] op_sel_hi:[1,0]
	v_pk_mul_f32 v[6:7], v[6:7], v[34:35] op_sel_hi:[1,0]
	v_pk_mul_f32 v[0:1], v[0:1], v[34:35] op_sel_hi:[1,0]
	v_pk_mul_f32 v[2:3], v[2:3], v[34:35] op_sel_hi:[1,0]
	v_cmp_lt_i32_e32 vcc, s45, v20
	s_or_b64 s[10:11], vcc, s[10:11]
	v_pk_add_f32 v[14:15], v[14:15], 1.0 op_sel_hi:[1,0]
	v_pk_add_f32 v[12:13], v[12:13], 1.0 op_sel_hi:[1,0]
	v_pk_fma_f32 v[10:11], v[14:15], v[10:11], v[18:19]
	v_pk_fma_f32 v[8:9], v[12:13], v[8:9], v[16:17]
	s_nop 0
	v_cvt_pk_bf16_f32 v8, v8, v9
	v_cvt_pk_bf16_f32 v9, v10, v11
	global_store_dwordx2 v[22:23], v[8:9], off offset:-1024
	s_nop 1
	v_mov_b64_e32 v[8:9], v[84:85]
	v_mov_b64_e32 v[10:11], v[86:87]
	s_nop 0
	v_mov_b64_e32 v[12:13], v[68:69]
	v_mov_b64_e32 v[14:15], v[70:71]
	v_pk_add_f32 v[10:11], v[10:11], 1.0 op_sel_hi:[1,0]
	v_pk_add_f32 v[8:9], v[8:9], 1.0 op_sel_hi:[1,0]
	v_pk_fma_f32 v[6:7], v[10:11], v[6:7], v[14:15]
	v_pk_fma_f32 v[4:5], v[8:9], v[4:5], v[12:13]
	s_nop 0
	v_cvt_pk_bf16_f32 v4, v4, v5
	v_cvt_pk_bf16_f32 v5, v6, v7
	global_store_dwordx2 v[22:23], v[4:5], off offset:-512
	s_nop 1
	v_mov_b64_e32 v[4:5], v[88:89]
	v_mov_b64_e32 v[6:7], v[90:91]
	s_nop 0
	v_mov_b64_e32 v[8:9], v[72:73]
	v_mov_b64_e32 v[10:11], v[74:75]
	v_pk_add_f32 v[6:7], v[6:7], 1.0 op_sel_hi:[1,0]
	v_pk_add_f32 v[4:5], v[4:5], 1.0 op_sel_hi:[1,0]
	v_pk_fma_f32 v[2:3], v[2:3], v[6:7], v[10:11]
	v_pk_fma_f32 v[0:1], v[0:1], v[4:5], v[8:9]
	s_nop 0
	v_cvt_pk_bf16_f32 v0, v0, v1
	v_cvt_pk_bf16_f32 v1, v2, v3
	global_store_dwordx2 v[22:23], v[0:1], off
	v_lshl_add_u64 v[22:23], v[22:23], 0, s[18:19]
	s_andn2_b64 exec, exec, s[10:11]
	s_cbranch_execnz .LBB0_418
